# move MoBA prep from phase 4 into phase 5 next to the GDN scan (raw k rows to a side buffer in d_out)
# speedup vs baseline: 1.0149x; 1.0149x over previous
_Z10hymba_mega6Params:
	s_load_dwordx4 s[68:71], s[0:1], 0x98
	s_load_dword s11, s[0:1], 0xa8
	s_load_dwordx2 s[98:99], s[0:1], 0x90
	s_add_u32 s16, s0, 0xa8
	s_mov_b32 s10, s2
	v_writelane_b32 v246, s0, 0
	s_addc_u32 s17, s1, 0
	s_waitcnt lgkmcnt(0)
	s_add_u32 s98, s98, 0x4000000
	s_addc_u32 s99, s99, 0
	s_cmpk_lt_i32 s71, 0x3e9
	v_writelane_b32 v246, s1, 1
	s_cbranch_scc1 .LBB0_12
	v_and_b32_e32 v1, 0x3fffffff, v0
	v_cmp_eq_u32_e32 vcc, 0, v1
	s_barrier
	s_and_saveexec_b64 s[2:3], vcc
	s_cbranch_execz .LBB0_11
	buffer_wbl2 sc1
	s_load_dwordx2 s[4:5], s[16:17], 0x58
	s_mov_b64 s[6:7], exec
	v_mbcnt_lo_u32_b32 v1, s6, 0
	v_mbcnt_hi_u32_b32 v1, s7, v1
	v_cmp_eq_u32_e32 vcc, 0, v1
	s_waitcnt lgkmcnt(0)
	s_load_dword s0, s[4:5], 0x28
	s_and_saveexec_b64 s[8:9], vcc
	s_cbranch_execz .LBB0_4
	s_bcnt1_i32_b64 s1, s[6:7]
	v_mov_b32_e32 v2, 0
	v_mov_b32_e32 v3, s1
	global_atomic_add v2, v2, v3, s[4:5] offset:32 sc0

.LBB0_206:
	ds_read_b128 v[148:151], v164
	ds_read_b128 v[152:155], v164 offset:1024
	ds_read_b128 v[156:159], v164 offset:2048
	ds_read_b128 v[168:171], v164 offset:3072
	s_add_u32 s38, s36, 0xfffc0080
	s_addc_u32 s39, s37, -1
	s_cmp_eq_u32 s60, 12
	s_cselect_b32 s41, s0, s39
	s_cselect_b32 s40, s1, s38
	s_cselect_b32 s39, s25, s59
	s_cselect_b32 s38, s27, s35
	v_lshl_add_u64 v[204:205], s[36:37], 0, v[140:141]
	s_add_i32 m0, s46, 0xc000
	ds_read_b128 v[172:175], v165
	ds_read_b128 v[176:179], v165 offset:1024
	ds_read_b128 v[180:183], v165 offset:2048
	ds_read_b128 v[184:187], v165 offset:3072
	ds_read_b128 v[188:191], v165 offset:4096
	ds_read_b128 v[192:195], v165 offset:5120
	ds_read_b128 v[196:199], v165 offset:6144
	ds_read_b128 v[200:203], v165 offset:7168
	global_load_lds_dwordx4 v[204:205], off
	v_lshl_add_u64 v[204:205], s[36:37], 0, v[142:143]
	s_add_i32 m0, s46, 0xe000
	s_nop 0
	global_load_lds_dwordx4 v[204:205], off
	s_waitcnt lgkmcnt(8)
	s_barrier
	s_waitcnt lgkmcnt(0)
	s_setprio 1
	s_waitcnt lgkmcnt(0)
	v_mfma_f32_16x16x32_bf16 v[126:129], v[148:151], v[172:175], v[126:129]
	v_mfma_f32_16x16x32_bf16 v[122:125], v[156:159], v[172:175], v[122:125]
	v_mfma_f32_16x16x32_bf16 v[110:113], v[148:151], v[180:183], v[110:113]
	v_mfma_f32_16x16x32_bf16 v[106:109], v[156:159], v[180:183], v[106:109]
	v_mfma_f32_16x16x32_bf16 v[94:97], v[148:151], v[188:191], v[94:97]
	v_mfma_f32_16x16x32_bf16 v[90:93], v[156:159], v[188:191], v[90:93]
	v_mfma_f32_16x16x32_bf16 v[78:81], v[148:151], v[196:199], v[78:81]
	v_mfma_f32_16x16x32_bf16 v[74:77], v[156:159], v[196:199], v[74:77]
	v_mfma_f32_16x16x32_bf16 v[126:129], v[152:155], v[176:179], v[126:129]
	v_mfma_f32_16x16x32_bf16 v[122:125], v[168:171], v[176:179], v[122:125]
	v_mfma_f32_16x16x32_bf16 v[110:113], v[152:155], v[184:187], v[110:113]
	v_mfma_f32_16x16x32_bf16 v[106:109], v[168:171], v[184:187], v[106:109]
	v_mfma_f32_16x16x32_bf16 v[94:97], v[152:155], v[192:195], v[94:97]
	v_mfma_f32_16x16x32_bf16 v[90:93], v[168:171], v[192:195], v[90:93]
	v_mfma_f32_16x16x32_bf16 v[78:81], v[152:155], v[200:203], v[78:81]
	v_mfma_f32_16x16x32_bf16 v[74:77], v[168:171], v[200:203], v[74:77]
	s_setprio 0
	s_barrier
	s_add_i32 s61, s55, s43
	v_lshl_add_u64 v[220:221], s[38:39], 0, v[132:133]
	s_mov_b32 m0, s61
	ds_read_b128 v[204:207], v166
	ds_read_b128 v[208:211], v166 offset:1024
	ds_read_b128 v[212:215], v166 offset:2048
	ds_read_b128 v[216:219], v166 offset:3072
	global_load_lds_dwordx4 v[220:221], off
	v_lshl_add_u64 v[222:223], s[38:39], 0, v[136:137]
	s_add_i32 m0, s61, 0x2000
	s_nop 0
	global_load_lds_dwordx4 v[222:223], off
	s_barrier
	s_waitcnt lgkmcnt(0)
	s_setprio 1
	s_waitcnt lgkmcnt(0)
	v_mfma_f32_16x16x32_bf16 v[118:121], v[204:207], v[172:175], v[118:121]
	v_mfma_f32_16x16x32_bf16 v[114:117], v[212:215], v[172:175], v[114:117]
	v_mfma_f32_16x16x32_bf16 v[102:105], v[204:207], v[180:183], v[102:105]
	v_mfma_f32_16x16x32_bf16 v[98:101], v[212:215], v[180:183], v[98:101]
	v_mfma_f32_16x16x32_bf16 v[86:89], v[204:207], v[188:191], v[86:89]
	v_mfma_f32_16x16x32_bf16 v[82:85], v[212:215], v[188:191], v[82:85]
	v_mfma_f32_16x16x32_bf16 v[70:73], v[204:207], v[196:199], v[70:73]
	v_mfma_f32_16x16x32_bf16 v[66:69], v[212:215], v[196:199], v[66:69]
	v_mfma_f32_16x16x32_bf16 v[118:121], v[208:211], v[176:179], v[118:121]
	v_mfma_f32_16x16x32_bf16 v[114:117], v[216:219], v[176:179], v[114:117]
	v_mfma_f32_16x16x32_bf16 v[102:105], v[208:211], v[184:187], v[102:105]
	v_mfma_f32_16x16x32_bf16 v[98:101], v[216:219], v[184:187], v[98:101]
	v_mfma_f32_16x16x32_bf16 v[86:89], v[208:211], v[192:195], v[86:89]
	v_mfma_f32_16x16x32_bf16 v[82:85], v[216:219], v[192:195], v[82:85]
	v_mfma_f32_16x16x32_bf16 v[70:73], v[208:211], v[200:203], v[70:73]
	v_mfma_f32_16x16x32_bf16 v[66:69], v[216:219], v[200:203], v[66:69]
	s_setprio 0
	s_mov_b32 m0, s46
	v_lshl_add_u64 v[224:225], s[40:41], 0, v[130:131]
	s_barrier
	ds_read_b128 v[172:175], v165 offset:16384
	ds_read_b128 v[176:179], v165 offset:17408
	ds_read_b128 v[180:183], v165 offset:18432
	ds_read_b128 v[184:187], v165 offset:19456
	ds_read_b128 v[188:191], v165 offset:20480
	ds_read_b128 v[192:195], v165 offset:21504
	ds_read_b128 v[196:199], v165 offset:22528
	ds_read_b128 v[200:203], v165 offset:23552
	global_load_lds_dwordx4 v[224:225], off
	v_lshl_add_u64 v[226:227], s[40:41], 0, v[134:135]
	s_mov_b32 m0, s47
	s_nop 0
	global_load_lds_dwordx4 v[226:227], off
	s_barrier
	s_waitcnt lgkmcnt(0)
	s_setprio 1
	s_waitcnt lgkmcnt(0)
	v_mfma_f32_16x16x32_bf16 v[62:65], v[148:151], v[172:175], v[62:65]
	v_mfma_f32_16x16x32_bf16 v[58:61], v[156:159], v[172:175], v[58:61]
	v_mfma_f32_16x16x32_bf16 v[46:49], v[148:151], v[180:183], v[46:49]
	v_mfma_f32_16x16x32_bf16 v[42:45], v[156:159], v[180:183], v[42:45]
	v_mfma_f32_16x16x32_bf16 v[30:33], v[148:151], v[188:191], v[30:33]
	v_mfma_f32_16x16x32_bf16 v[26:29], v[156:159], v[188:191], v[26:29]
	v_mfma_f32_16x16x32_bf16 v[14:17], v[148:151], v[196:199], v[14:17]
	v_mfma_f32_16x16x32_bf16 v[10:13], v[156:159], v[196:199], v[10:13]
	v_mfma_f32_16x16x32_bf16 v[62:65], v[152:155], v[176:179], v[62:65]
	v_mfma_f32_16x16x32_bf16 v[58:61], v[168:171], v[176:179], v[58:61]
	v_mfma_f32_16x16x32_bf16 v[46:49], v[152:155], v[184:187], v[46:49]
	v_mfma_f32_16x16x32_bf16 v[42:45], v[168:171], v[184:187], v[42:45]
	v_mfma_f32_16x16x32_bf16 v[30:33], v[152:155], v[192:195], v[30:33]
	v_mfma_f32_16x16x32_bf16 v[26:29], v[168:171], v[192:195], v[26:29]
	v_mfma_f32_16x16x32_bf16 v[14:17], v[152:155], v[200:203], v[14:17]
	v_mfma_f32_16x16x32_bf16 v[10:13], v[168:171], v[200:203], v[10:13]
	s_setprio 0
	s_barrier
	s_add_u32 s62, s38, 0x40000
	s_addc_u32 s63, s39, 0
	s_add_i32 s61, s56, s43
	v_lshl_add_u64 v[148:149], s[62:63], 0, v[132:133]
	s_mov_b32 m0, s61
	s_nop 0
	global_load_lds_dwordx4 v[148:149], off
	v_lshl_add_u64 v[148:149], s[62:63], 0, v[136:137]
	s_add_i32 m0, s61, 0x2000
	s_nop 0
	global_load_lds_dwordx4 v[148:149], off
	s_waitcnt vmcnt(6)
	s_barrier
	s_setprio 1
	v_mfma_f32_16x16x32_bf16 v[54:57], v[204:207], v[172:175], v[54:57]
	v_mfma_f32_16x16x32_bf16 v[50:53], v[212:215], v[172:175], v[50:53]
	v_mfma_f32_16x16x32_bf16 v[38:41], v[204:207], v[180:183], v[38:41]
	v_mfma_f32_16x16x32_bf16 v[34:37], v[212:215], v[180:183], v[34:37]
	v_mfma_f32_16x16x32_bf16 v[22:25], v[204:207], v[188:191], v[22:25]
	v_mfma_f32_16x16x32_bf16 v[18:21], v[212:215], v[188:191], v[18:21]
	v_mfma_f32_16x16x32_bf16 v[6:9], v[204:207], v[196:199], v[6:9]
	v_mfma_f32_16x16x32_bf16 v[2:5], v[212:215], v[196:199], v[2:5]
	v_mfma_f32_16x16x32_bf16 v[54:57], v[208:211], v[176:179], v[54:57]
	v_mfma_f32_16x16x32_bf16 v[50:53], v[216:219], v[176:179], v[50:53]
	v_mfma_f32_16x16x32_bf16 v[38:41], v[208:211], v[184:187], v[38:41]
	v_mfma_f32_16x16x32_bf16 v[34:37], v[216:219], v[184:187], v[34:37]
	v_mfma_f32_16x16x32_bf16 v[22:25], v[208:211], v[192:195], v[22:25]
	v_mfma_f32_16x16x32_bf16 v[18:21], v[216:219], v[192:195], v[18:21]
	v_mfma_f32_16x16x32_bf16 v[6:9], v[208:211], v[200:203], v[6:9]
	v_mfma_f32_16x16x32_bf16 v[2:5], v[216:219], v[200:203], v[2:5]
	s_setprio 0
	s_add_i32 s61, 0, 0x18000
	v_add_u32_e32 v138, s61, v161
	s_barrier
	ds_read_b128 v[148:151], v138
	ds_read_b128 v[152:155], v138 offset:1024
	ds_read_b128 v[156:159], v138 offset:2048
	ds_read_b128 v[168:171], v138 offset:3072
	s_add_u32 s40, s40, 0x40000
	s_addc_u32 s41, s41, 0
	s_mov_b32 m0, s48
	v_lshl_add_u64 v[204:205], s[40:41], 0, v[130:131]
	ds_read_b128 v[172:175], v165 offset:32768
	ds_read_b128 v[176:179], v165 offset:33792
	ds_read_b128 v[180:183], v165 offset:34816
	ds_read_b128 v[184:187], v165 offset:35840
	ds_read_b128 v[188:191], v165 offset:36864
	ds_read_b128 v[192:195], v165 offset:37888
	ds_read_b128 v[196:199], v165 offset:38912
	ds_read_b128 v[200:203], v165 offset:39936
	global_load_lds_dwordx4 v[204:205], off
	v_lshl_add_u64 v[204:205], s[40:41], 0, v[134:135]
	s_mov_b32 m0, s49
	s_nop 0
	global_load_lds_dwordx4 v[204:205], off
	s_waitcnt lgkmcnt(8)
	s_barrier
	s_waitcnt lgkmcnt(0)
	s_setprio 1
	s_waitcnt lgkmcnt(0)
	v_mfma_f32_16x16x32_bf16 v[126:129], v[148:151], v[172:175], v[126:129]
	v_mfma_f32_16x16x32_bf16 v[122:125], v[156:159], v[172:175], v[122:125]
	v_mfma_f32_16x16x32_bf16 v[110:113], v[148:151], v[180:183], v[110:113]
	v_mfma_f32_16x16x32_bf16 v[106:109], v[156:159], v[180:183], v[106:109]
	v_mfma_f32_16x16x32_bf16 v[94:97], v[148:151], v[188:191], v[94:97]
	v_mfma_f32_16x16x32_bf16 v[90:93], v[156:159], v[188:191], v[90:93]
	v_mfma_f32_16x16x32_bf16 v[78:81], v[148:151], v[196:199], v[78:81]
	v_mfma_f32_16x16x32_bf16 v[74:77], v[156:159], v[196:199], v[74:77]
	v_mfma_f32_16x16x32_bf16 v[126:129], v[152:155], v[176:179], v[126:129]
	v_mfma_f32_16x16x32_bf16 v[122:125], v[168:171], v[176:179], v[122:125]
	v_mfma_f32_16x16x32_bf16 v[110:113], v[152:155], v[184:187], v[110:113]
	v_mfma_f32_16x16x32_bf16 v[106:109], v[168:171], v[184:187], v[106:109]
	v_mfma_f32_16x16x32_bf16 v[94:97], v[152:155], v[192:195], v[94:97]
	v_mfma_f32_16x16x32_bf16 v[90:93], v[168:171], v[192:195], v[90:93]
	v_mfma_f32_16x16x32_bf16 v[78:81], v[152:155], v[200:203], v[78:81]
	v_mfma_f32_16x16x32_bf16 v[74:77], v[168:171], v[200:203], v[74:77]
	s_setprio 0
	s_barrier
	s_add_i32 s40, 0, 0x1c000
	s_add_i32 s41, s61, s43
	v_add_u32_e32 v138, s40, v161
	v_lshl_add_u64 v[220:221], v[220:221], 0, s[12:13]
	s_mov_b32 m0, s41
	ds_read_b128 v[204:207], v138
	ds_read_b128 v[208:211], v138 offset:1024
	ds_read_b128 v[212:215], v138 offset:2048
	ds_read_b128 v[216:219], v138 offset:3072
	global_load_lds_dwordx4 v[220:221], off
	v_lshl_add_u64 v[220:221], v[222:223], 0, s[12:13]
	s_add_i32 m0, s41, 0x2000
	s_nop 0
	global_load_lds_dwordx4 v[220:221], off
	s_barrier
	s_waitcnt lgkmcnt(0)
	s_setprio 1
	s_waitcnt lgkmcnt(0)
	v_mfma_f32_16x16x32_bf16 v[118:121], v[204:207], v[172:175], v[118:121]
	v_mfma_f32_16x16x32_bf16 v[114:117], v[212:215], v[172:175], v[114:117]
	v_mfma_f32_16x16x32_bf16 v[102:105], v[204:207], v[180:183], v[102:105]
	v_mfma_f32_16x16x32_bf16 v[98:101], v[212:215], v[180:183], v[98:101]
	v_mfma_f32_16x16x32_bf16 v[86:89], v[204:207], v[188:191], v[86:89]
	v_mfma_f32_16x16x32_bf16 v[82:85], v[212:215], v[188:191], v[82:85]
	v_mfma_f32_16x16x32_bf16 v[70:73], v[204:207], v[196:199], v[70:73]
	v_mfma_f32_16x16x32_bf16 v[66:69], v[212:215], v[196:199], v[66:69]
	v_mfma_f32_16x16x32_bf16 v[118:121], v[208:211], v[176:179], v[118:121]
	v_mfma_f32_16x16x32_bf16 v[114:117], v[216:219], v[176:179], v[114:117]
	v_mfma_f32_16x16x32_bf16 v[102:105], v[208:211], v[184:187], v[102:105]
	v_mfma_f32_16x16x32_bf16 v[98:101], v[216:219], v[184:187], v[98:101]
	v_mfma_f32_16x16x32_bf16 v[86:89], v[208:211], v[192:195], v[86:89]
	v_mfma_f32_16x16x32_bf16 v[82:85], v[216:219], v[192:195], v[82:85]
	v_mfma_f32_16x16x32_bf16 v[70:73], v[208:211], v[200:203], v[70:73]
	v_mfma_f32_16x16x32_bf16 v[66:69], v[216:219], v[200:203], v[66:69]
	s_setprio 0
	s_mov_b32 m0, s50
	v_lshl_add_u64 v[220:221], v[224:225], 0, s[12:13]
	s_barrier
	ds_read_b128 v[172:175], v165 offset:49152
	ds_read_b128 v[176:179], v165 offset:50176
	ds_read_b128 v[180:183], v165 offset:51200
	ds_read_b128 v[184:187], v165 offset:52224
	ds_read_b128 v[188:191], v165 offset:53248
	ds_read_b128 v[192:195], v165 offset:54272
	ds_read_b128 v[196:199], v165 offset:55296
	ds_read_b128 v[200:203], v165 offset:56320
	global_load_lds_dwordx4 v[220:221], off
	v_lshl_add_u64 v[220:221], v[226:227], 0, s[12:13]
	s_mov_b32 m0, s51
	s_nop 0
	global_load_lds_dwordx4 v[220:221], off
	s_barrier
	s_waitcnt lgkmcnt(0)
	s_setprio 1
	s_waitcnt lgkmcnt(0)
	v_mfma_f32_16x16x32_bf16 v[62:65], v[148:151], v[172:175], v[62:65]
	v_mfma_f32_16x16x32_bf16 v[58:61], v[156:159], v[172:175], v[58:61]
	v_mfma_f32_16x16x32_bf16 v[46:49], v[148:151], v[180:183], v[46:49]
	v_mfma_f32_16x16x32_bf16 v[42:45], v[156:159], v[180:183], v[42:45]
	v_mfma_f32_16x16x32_bf16 v[30:33], v[148:151], v[188:191], v[30:33]
	v_mfma_f32_16x16x32_bf16 v[26:29], v[156:159], v[188:191], v[26:29]
	v_mfma_f32_16x16x32_bf16 v[14:17], v[148:151], v[196:199], v[14:17]
	v_mfma_f32_16x16x32_bf16 v[10:13], v[156:159], v[196:199], v[10:13]
	v_mfma_f32_16x16x32_bf16 v[62:65], v[152:155], v[176:179], v[62:65]
	v_mfma_f32_16x16x32_bf16 v[58:61], v[168:171], v[176:179], v[58:61]
	v_mfma_f32_16x16x32_bf16 v[46:49], v[152:155], v[184:187], v[46:49]
	v_mfma_f32_16x16x32_bf16 v[42:45], v[168:171], v[184:187], v[42:45]
	v_mfma_f32_16x16x32_bf16 v[30:33], v[152:155], v[192:195], v[30:33]
	v_mfma_f32_16x16x32_bf16 v[26:29], v[168:171], v[192:195], v[26:29]
	v_mfma_f32_16x16x32_bf16 v[14:17], v[152:155], v[200:203], v[14:17]
	v_mfma_f32_16x16x32_bf16 v[10:13], v[168:171], v[200:203], v[10:13]
	s_setprio 0
	s_barrier
	s_add_u32 s38, s38, 0x40080
	s_addc_u32 s39, s39, 0
	s_add_i32 s40, s40, s43
	v_lshl_add_u64 v[148:149], s[38:39], 0, v[132:133]
	s_mov_b32 m0, s40
	s_nop 0
	global_load_lds_dwordx4 v[148:149], off
	v_lshl_add_u64 v[148:149], s[38:39], 0, v[136:137]
	s_add_i32 m0, s40, 0x2000
	s_nop 0
	global_load_lds_dwordx4 v[148:149], off
	s_waitcnt vmcnt(6)
	s_barrier
	s_setprio 1
	v_mfma_f32_16x16x32_bf16 v[54:57], v[204:207], v[172:175], v[54:57]
	v_mfma_f32_16x16x32_bf16 v[50:53], v[212:215], v[172:175], v[50:53]
	v_mfma_f32_16x16x32_bf16 v[38:41], v[204:207], v[180:183], v[38:41]
	v_mfma_f32_16x16x32_bf16 v[34:37], v[212:215], v[180:183], v[34:37]
	v_mfma_f32_16x16x32_bf16 v[22:25], v[204:207], v[188:191], v[22:25]
	v_mfma_f32_16x16x32_bf16 v[18:21], v[212:215], v[188:191], v[18:21]
	v_mfma_f32_16x16x32_bf16 v[6:9], v[204:207], v[196:199], v[6:9]
	v_mfma_f32_16x16x32_bf16 v[2:5], v[212:215], v[196:199], v[2:5]
	v_mfma_f32_16x16x32_bf16 v[54:57], v[208:211], v[176:179], v[54:57]
	v_mfma_f32_16x16x32_bf16 v[50:53], v[216:219], v[176:179], v[50:53]
	v_mfma_f32_16x16x32_bf16 v[38:41], v[208:211], v[184:187], v[38:41]
	v_mfma_f32_16x16x32_bf16 v[34:37], v[216:219], v[184:187], v[34:37]
	v_mfma_f32_16x16x32_bf16 v[22:25], v[208:211], v[192:195], v[22:25]
	v_mfma_f32_16x16x32_bf16 v[18:21], v[216:219], v[192:195], v[18:21]
	v_mfma_f32_16x16x32_bf16 v[6:9], v[208:211], v[200:203], v[6:9]
	v_mfma_f32_16x16x32_bf16 v[2:5], v[216:219], v[200:203], v[2:5]
	s_setprio 0
	s_add_i32 s60, s60, 2
	s_add_u32 s36, s36, 0x100
	s_addc_u32 s37, s37, 0
	s_add_u32 s35, s35, 0x100
	s_addc_u32 s59, s59, 0
	s_cmp_gt_u32 s60, 13
	s_barrier
	s_cbranch_scc0 .LBB0_206
	s_add_u32 s8, s68, 0xf000000
	s_addc_u32 s9, s69, 0
	s_cmp_gt_i32 s4, 11
	s_cselect_b32 s8, s8, s98
	s_cselect_b32 s9, s9, s99
	s_cmp_gt_i32 s4, 9
	v_lshl_add_u32 v150, s34, 8, v160
	s_cselect_b64 s[34:35], -1, 0
	s_lshl_b32 s0, s5, 10
	v_add_u32_e32 v167, s0, v162
	ds_read_b32 v152, v167
	v_ashrrev_i32_e32 v151, 31, v150
	v_lshlrev_b64 v[154:155], 11, v[150:151]
	v_lshl_or_b32 v148, s4, 8, v163
	s_mov_b64 s[4:5], -1
	s_and_b64 vcc, exec, s[34:35]
	v_lshl_add_u64 v[154:155], s[8:9], 0, v[154:155]
	s_cbranch_vccz .LBB0_209
	v_mov_b32_e32 v149, v139
	v_lshl_add_u64 v[156:157], v[148:149], 1, v[154:155]
	v_lshl_add_u64 v[158:159], v[156:157], 0, s[20:21]
	s_mov_b64 s[4:5], 0

.LBB0_385:
	s_andn2_saveexec_b64 s[2:3], s[2:3]
	s_cbranch_execz .LBB0_295
	v_lshlrev_b32_e32 v3, 11, v142
	v_add3_u32 v3, v140, v3, v141
	v_cvt_pk_bf16_f32 v6, v6, v7
	v_cvt_pk_bf16_f32 v7, v8, v9
	v_cvt_pk_bf16_f32 v8, v14, v15
	v_cvt_pk_bf16_f32 v9, v18, v19
	v_add_u32_e32 v3, 0x4000, v3
	ds_write2_b64 v3, v[6:7], v[8:9] offset1:16
	v_cvt_pk_bf16_f32 v6, v24, v25
	v_cvt_pk_bf16_f32 v7, v26, v27
	v_cvt_pk_bf16_f32 v8, v32, v33
	v_cvt_pk_bf16_f32 v9, v34, v35
	ds_write2_b64 v3, v[6:7], v[8:9] offset0:32 offset1:48
	v_cvt_pk_bf16_f32 v6, v40, v41
	v_cvt_pk_bf16_f32 v7, v42, v43
	v_cvt_pk_bf16_f32 v8, v48, v49
	v_cvt_pk_bf16_f32 v9, v50, v51
	ds_write2_b64 v3, v[6:7], v[8:9] offset0:64 offset1:80
	v_cvt_pk_bf16_f32 v6, v56, v57
	v_cvt_pk_bf16_f32 v7, v62, v63
	v_cvt_pk_bf16_f32 v8, v68, v69
	v_cvt_pk_bf16_f32 v9, v70, v71
	ds_write2_b64 v3, v[6:7], v[8:9] offset0:96 offset1:112
	v_cvt_pk_bf16_f32 v6, v76, v77
	v_cvt_pk_bf16_f32 v7, v78, v79
	v_cvt_pk_bf16_f32 v8, v84, v85
	v_cvt_pk_bf16_f32 v9, v86, v87
	ds_write2_b64 v3, v[6:7], v[8:9] offset0:128 offset1:144
	v_cvt_pk_bf16_f32 v6, v92, v93
	v_cvt_pk_bf16_f32 v7, v94, v95
	v_cvt_pk_bf16_f32 v8, v100, v101
	v_cvt_pk_bf16_f32 v9, v102, v103
	ds_write2_b64 v3, v[6:7], v[8:9] offset0:160 offset1:176
	v_cvt_pk_bf16_f32 v6, v108, v109
	v_cvt_pk_bf16_f32 v7, v110, v111
	v_cvt_pk_bf16_f32 v8, v116, v117
	v_cvt_pk_bf16_f32 v9, v118, v119
	ds_write2_b64 v3, v[6:7], v[8:9] offset0:192 offset1:208
	v_cvt_pk_bf16_f32 v6, v124, v125
	v_cvt_pk_bf16_f32 v7, v126, v127
	v_cvt_pk_bf16_f32 v8, v132, v133
	v_cvt_pk_bf16_f32 v9, v2, v4
	ds_write2_b64 v3, v[6:7], v[8:9] offset0:224 offset1:240
	s_branch .LBB0_295
.LBB0_387:
	s_branch .LBB0_404
.Lmp_entry:
	v_lshrrev_b32_e32 v140, 1, v1
	v_and_b32_e32 v4, 24, v1
	v_lshrrev_b32_e32 v5, 3, v1
	v_lshlrev_b32_e32 v2, 5, v1
	v_and_b32_e32 v3, 0x1e0, v140
	v_and_b32_e32 v5, 4, v5
	v_and_or_b32 v4, v140, 3, v4
	v_and_b32_e32 v2, 32, v2
	v_or3_b32 v3, v4, v5, v3
	v_mul_u32_u24_e32 v4, 0x210, v2
	s_add_i32 s0, 0, 0x10400
	v_lshlrev_b32_e32 v3, 1, v3
	v_add3_u32 v141, s0, v4, v3
	s_movk_i32 s1, 0xff
	v_and_b32_e32 v4, 63, v1
	v_cmp_lt_u32_e64 s[2:3], s1, v1
	s_movk_i32 s1, 0x104
	v_and_b32_e32 v5, 0xc0, v1
	v_lshl_add_u32 v7, v4, 2, 0
	v_mad_u32_u24 v142, v5, s1, v7
	v_lshlrev_b32_e32 v5, 4, v1
	v_and_b32_e32 v98, 0x1f0, v5
	v_add_u32_e32 v11, s0, v98
	s_load_dword s0, s[16:17], 0x10
	s_movk_i32 s4, 0x100
	v_and_b32_e32 v3, 0x300, v1
	v_readlane_b32 s8, v246, 0
	v_cmp_gt_u32_e32 vcc, s4, v1
	v_cmp_eq_u32_e64 s[4:5], s4, v3
	v_mul_u32_u24_sdwa v3, v1, s1 dst_sel:DWORD dst_unused:UNUSED_PAD src0_sel:BYTE_0 src1_sel:DWORD
	s_add_i32 s1, 0, 0x18800
	v_readlane_b32 s9, v246, 1
	v_lshrrev_b32_e32 v5, 5, v1
	s_add_u32 s22, s8, 0x60
	s_load_dwordx4 s[12:15], s[8:9], 0x90
	v_or_b32_e32 v4, 63, v1
	v_mul_u32_u24_e32 v13, 0x210, v5
	v_lshlrev_b32_e32 v6, 8, v5
	v_add_u32_e32 v5, 0x200, v1
	s_addc_u32 s23, s9, 0
	s_waitcnt lgkmcnt(0)
	s_lshr_b32 s0, s0, 16
	v_mul_u32_u24_e32 v9, 0x104, v4
	v_lshlrev_b32_e32 v4, 2, v1
	v_lshrrev_b32_e32 v5, 5, v5
	s_cmp_lg_u32 s0, 0
	v_add_u32_e32 v143, s1, v4
	v_mul_u32_u24_e32 v16, 0x210, v5
	v_lshlrev_b32_e32 v8, 8, v5
	v_add_u32_e32 v5, 0x600, v1
	s_cselect_b64 s[0:1], -1, 0
	v_mov_b32_e32 v99, 0
	v_lshrrev_b32_e32 v5, 5, v5
	s_cmp_lg_u64 s[0:1], 0
	v_mul_u32_u24_e32 v17, 0x210, v5
	v_lshlrev_b32_e32 v12, 8, v5
	s_addc_u32 s33, s11, 0
	s_sub_i32 s33, s33, 32
	v_lshl_add_u64 v[14:15], s[12:13], 0, v[98:99]
	s_mov_b64 s[0:1], 0x2000000
	v_mov_b32_e32 v5, v99
	v_or_b32_e32 v10, 0x2000, v6
	s_add_u32 s24, s14, 0xf000000
	v_lshl_add_u64 v[100:101], v[14:15], 0, s[0:1]
	v_lshl_add_u64 v[4:5], s[14:15], 0, v[4:5]
	s_mov_b64 s[0:1], 0x1eb68000
	s_mov_b32 s30, 0x6dc9c883
	s_mov_b32 s21, 0
	v_cmp_gt_u32_e64 s[6:7], 64, v1
	s_addc_u32 s25, s15, 0
	v_lshl_add_u64 v[102:103], v[4:5], 0, s[0:1]
	s_sub_i32 s36, s10, 32
	s_lshl_b32 s36, s36, 5
	s_lshl_b32 s37, s33, 5
	v_lshlrev_b32_e32 v104, 1, v2
	v_mov_b32_e32 v105, v99
	s_movk_i32 s38, 0x1400
	s_mov_b64 s[26:27], 0x4001000
	s_mov_b64 s[28:29], 0x400
	s_mov_b32 s31, 0x3fc45f30
	v_mov_b32_e32 v144, 0x358637bd
	s_mov_b32 s39, 0x800000
	v_add_u32_e32 v145, 0, v3
	v_add_u32_e32 v146, v7, v9
	v_add_u32_e32 v147, v11, v13
	v_lshlrev_b32_e32 v98, 1, v6
	v_add_u32_e32 v148, v11, v16
	v_lshlrev_b32_e32 v106, 1, v8
	v_lshlrev_b32_e32 v108, 1, v10
	v_add_u32_e32 v149, v11, v17
	v_lshlrev_b32_e32 v110, 1, v12
	s_sub_i32 s0, s10, 32
	s_branch .LBB0_390

.LBB0_390:
	s_bfe_u32 s1, s0, 0x40003
	s_and_b32 s8, s36, 0xfffff000
	s_lshl_b32 s35, s1, 8
	s_or_b32 s40, s35, s8
	v_add_u32_e32 v2, s40, v140
	v_ashrrev_i32_e32 v3, 31, v2
	s_and_b32 s34, s0, 7
	v_lshlrev_b64 v[2:3], 11, v[2:3]
	v_lshl_add_u64 v[2:3], s[24:25], 0, v[2:3]
	s_lshl_b32 s20, s34, 7
	v_lshl_add_u64 v[2:3], v[2:3], 0, s[20:21]
	v_lshl_add_u64 v[18:19], v[2:3], 0, v[104:105]
	global_load_dwordx4 v[2:5], v[18:19], off offset:1024
	global_load_dwordx4 v[6:9], v[18:19], off offset:1040
	global_load_dwordx4 v[10:13], v[18:19], off offset:1056
	global_load_dwordx4 v[14:17], v[18:19], off offset:1072
	v_or_b32_sdwa v114, s40, v1 dst_sel:DWORD dst_unused:UNUSED_PAD src0_sel:DWORD src1_sel:BYTE_0
	v_ashrrev_i32_e32 v115, 31, v114
	s_waitcnt vmcnt(0)
	ds_write_b16 v141, v2
	ds_write_b16_d16_hi v141, v2 offset:528
	ds_write_b16 v141, v3 offset:1056
	ds_write_b16_d16_hi v141, v3 offset:1584
	ds_write_b16 v141, v4 offset:2112
	ds_write_b16_d16_hi v141, v4 offset:2640
	ds_write_b16 v141, v5 offset:3168
	ds_write_b16_d16_hi v141, v5 offset:3696
	ds_write_b16 v141, v6 offset:4224
	ds_write_b16_d16_hi v141, v6 offset:4752
	ds_write_b16 v141, v7 offset:5280
	ds_write_b16_d16_hi v141, v7 offset:5808
	ds_write_b16 v141, v8 offset:6336
	ds_write_b16_d16_hi v141, v8 offset:6864
	ds_write_b16 v141, v9 offset:7392
	ds_write_b16_d16_hi v141, v9 offset:7920
	ds_write_b16 v141, v10 offset:8448
	ds_write_b16_d16_hi v141, v10 offset:8976
	ds_write_b16 v141, v11 offset:9504
	ds_write_b16_d16_hi v141, v11 offset:10032
	ds_write_b16 v141, v12 offset:10560
	ds_write_b16_d16_hi v141, v12 offset:11088
	ds_write_b16 v141, v13 offset:11616
	ds_write_b16_d16_hi v141, v13 offset:12144
	ds_write_b16 v141, v14 offset:12672
	ds_write_b16_d16_hi v141, v14 offset:13200
	ds_write_b16 v141, v15 offset:13728
	ds_write_b16_d16_hi v141, v15 offset:14256
	ds_write_b16 v141, v16 offset:14784
	ds_write_b16_d16_hi v141, v16 offset:15312
	ds_write_b16 v141, v17 offset:15840
	ds_write_b16_d16_hi v141, v17 offset:16368
	s_waitcnt lgkmcnt(0)
	s_barrier
	s_and_saveexec_b64 s[8:9], s[2:3]
	s_xor_b64 s[8:9], exec, s[8:9]
	v_lshlrev_b64 v[2:3], 11, v[114:115]
	v_lshl_add_u64 v[2:3], s[98:99], 0, v[2:3]
	s_or_saveexec_b64 s[8:9], s[8:9]
	v_mov_b64_e32 v[4:5], s[22:23]
	v_or_b32_e32 v116, s40, v1
	s_xor_b64 exec, exec, s[8:9]
	v_mov_b64_e32 v[2:3], s[14:15]
	v_mad_i64_i32 v[2:3], s[40:41], v116, s38, v[2:3]
	v_lshl_add_u64 v[2:3], v[2:3], 0, s[26:27]
	v_mov_b64_e32 v[4:5], s[18:19]
	s_or_b64 exec, exec, s[8:9]
	global_load_dwordx2 v[112:113], v[4:5], off
	s_lshl_b32 s8, s34, 6
	s_lshl_b32 s20, s8, 1
	v_lshl_add_u64 v[2:3], v[2:3], 0, s[20:21]
	global_load_dwordx4 v[82:85], v[2:3], off offset:48
	global_load_dwordx4 v[86:89], v[2:3], off offset:32
	global_load_dwordx4 v[90:93], v[2:3], off offset:16
	global_load_dwordx4 v[94:97], v[2:3], off
	global_load_dwordx4 v[66:69], v[2:3], off offset:112
	global_load_dwordx4 v[70:73], v[2:3], off offset:96
	global_load_dwordx4 v[74:77], v[2:3], off offset:80
	global_load_dwordx4 v[78:81], v[2:3], off offset:64
	s_waitcnt vmcnt(8)
	global_load_dwordx4 v[46:49], v[112:113], off offset:48
	global_load_dwordx4 v[54:57], v[112:113], off offset:32
	global_load_dwordx4 v[58:61], v[112:113], off offset:16
	global_load_dwordx4 v[62:65], v[112:113], off
	global_load_dwordx4 v[30:33], v[112:113], off offset:112
	global_load_dwordx4 v[38:41], v[112:113], off offset:96
	global_load_dwordx4 v[42:45], v[112:113], off offset:80
	global_load_dwordx4 v[50:53], v[112:113], off offset:64
	global_load_dwordx4 v[14:17], v[112:113], off offset:176
	global_load_dwordx4 v[22:25], v[112:113], off offset:160
	global_load_dwordx4 v[26:29], v[112:113], off offset:144
	global_load_dwordx4 v[34:37], v[112:113], off offset:128
	global_load_dwordx4 v[2:5], v[112:113], off offset:240
	global_load_dwordx4 v[6:9], v[112:113], off offset:224
	global_load_dwordx4 v[10:13], v[112:113], off offset:208
	global_load_dwordx4 v[18:21], v[112:113], off offset:192
	s_and_saveexec_b64 s[8:9], s[2:3]
	s_xor_b64 s[8:9], exec, s[8:9]
	v_lshlrev_b64 v[112:113], 10, v[114:115]
	v_lshl_add_u64 v[112:113], s[12:13], 0, v[112:113]
	s_andn2_saveexec_b64 s[8:9], s[8:9]
	v_ashrrev_i32_e32 v117, 31, v116
	v_lshlrev_b64 v[112:113], 11, v[116:117]
	v_lshl_add_u64 v[112:113], s[24:25], 0, v[112:113]
	v_lshl_add_u64 v[112:113], v[112:113], 0, s[28:29]
	s_or_b64 exec, exec, s[8:9]
	v_or_b32_sdwa v107, s35, v1 dst_sel:DWORD dst_unused:UNUSED_PAD src0_sel:DWORD src1_sel:BYTE_0
	v_cvt_f64_u32_e32 v[114:115], v107
	v_cvt_f32_u32_e32 v109, v107
	v_mul_f64 v[116:117], v[114:115], s[30:31]
	v_rndne_f64_e32 v[116:117], v[116:117]
	v_fma_f64 v[114:115], v[114:115], s[30:31], -v[116:117]
	v_cvt_f32_f64_e32 v107, v[114:115]
	v_sin_f32_e32 v114, v107
	v_cos_f32_e32 v116, v107
	v_mul_f32_e32 v107, 0x3e4693af, v109
	v_cvt_f64_f32_e32 v[118:119], v107
	v_mul_f64 v[120:121], v[118:119], s[30:31]
	v_rndne_f64_e32 v[120:121], v[120:121]
	v_fma_f64 v[118:119], v[118:119], s[30:31], -v[120:121]
	s_waitcnt vmcnt(21)
	v_lshlrev_b32_e32 v122, 16, v90
	v_and_b32_e32 v123, 0xffff0000, v90
	v_mul_f32_e32 v90, 0x3d1a08c8, v109
	v_cvt_f32_f64_e32 v107, v[118:119]
	v_cvt_f64_f32_e32 v[118:119], v90
	v_mul_f64 v[120:121], v[118:119], s[30:31]
	v_rndne_f64_e32 v[120:121], v[120:121]
	v_fma_f64 v[118:119], v[118:119], s[30:31], -v[120:121]
	v_cvt_f32_f64_e32 v90, v[118:119]
	v_sin_f32_e32 v118, v90
	v_cos_f32_e32 v120, v90
	v_mul_f32_e32 v90, 0x3beef74e, v109
	v_cvt_f64_f32_e32 v[126:127], v90
	v_mul_f64 v[128:129], v[126:127], s[30:31]
	v_rndne_f64_e32 v[128:129], v[128:129]
	v_fma_f64 v[126:127], v[126:127], s[30:31], -v[128:129]
	v_cvt_f32_f64_e32 v90, v[126:127]
	v_sin_f32_e32 v119, v90
	v_cos_f32_e32 v121, v90
	v_mul_f32_e32 v90, 0x3ab95d22, v109
	v_lshlrev_b32_e32 v126, 16, v91
	v_and_b32_e32 v127, 0xffff0000, v91
	v_cvt_f64_f32_e32 v[90:91], v90
	s_waitcnt vmcnt(20)
	v_lshlrev_b32_e32 v124, 16, v94
	v_and_b32_e32 v125, 0xffff0000, v94
	v_lshlrev_b32_e32 v128, 16, v95
	v_and_b32_e32 v129, 0xffff0000, v95
	v_mul_f64 v[94:95], v[90:91], s[30:31]
	v_rndne_f64_e32 v[94:95], v[94:95]
	v_fma_f64 v[90:91], v[90:91], s[30:31], -v[94:95]
	v_cvt_f32_f64_e32 v91, v[90:91]
	v_sin_f32_e32 v90, v91
	v_cos_f32_e32 v94, v91
	v_mul_f32_e32 v91, 0x398fc8f8, v109
	v_cvt_f64_f32_e32 v[130:131], v91
	v_mul_f64 v[132:133], v[130:131], s[30:31]
	v_rndne_f64_e32 v[132:133], v[132:133]
	v_fma_f64 v[130:131], v[130:131], s[30:31], -v[132:133]
	v_cvt_f32_f64_e32 v95, v[130:131]
	v_lshlrev_b32_e32 v130, 16, v92
	v_and_b32_e32 v131, 0xffff0000, v92
	v_mul_f32_e32 v92, 0x385f10c5, v109
	v_cvt_f64_f32_e32 v[138:139], v92
	v_mul_f64 v[158:159], v[138:139], s[30:31]
	v_rndne_f64_e32 v[158:159], v[158:159]
	v_sin_f32_e32 v115, v107
	v_cos_f32_e32 v117, v107
	v_fma_f64 v[138:139], v[138:139], s[30:31], -v[158:159]
	v_mul_f32_e32 v107, 0x372d07a8, v109
	v_lshlrev_b32_e32 v132, 16, v96
	v_and_b32_e32 v133, 0xffff0000, v96
	v_cvt_f32_f64_e32 v96, v[138:139]
	v_cvt_f64_f32_e32 v[138:139], v107
	v_mul_f64 v[158:159], v[138:139], s[30:31]
	v_pk_mul_f32 v[136:137], v[124:125], v[124:125]
	v_rndne_f64_e32 v[158:159], v[158:159]
	v_pk_mul_f32 v[150:151], v[128:129], v[128:129]
	v_fma_f64 v[158:159], v[138:139], s[30:31], -v[158:159]
	v_lshlrev_b32_e32 v138, 16, v93
	v_and_b32_e32 v139, 0xffff0000, v93
	v_add_f32_e32 v93, v136, v137
	v_add_f32_e32 v93, v150, v93
	v_pk_mul_f32 v[154:155], v[132:133], v[132:133]
	v_add_f32_e32 v93, v151, v93
	v_lshlrev_b32_e32 v160, 16, v97
	v_and_b32_e32 v161, 0xffff0000, v97
	v_add_f32_e32 v93, v154, v93
	v_pk_mul_f32 v[162:163], v[160:161], v[160:161]
	v_add_f32_e32 v93, v155, v93
	v_add_f32_e32 v93, v162, v93
	v_pk_mul_f32 v[134:135], v[122:123], v[122:123]
	v_add_f32_e32 v93, v163, v93
	v_add_f32_e32 v93, v134, v93
	v_pk_mul_f32 v[152:153], v[126:127], v[126:127]
	v_add_f32_e32 v93, v135, v93
	v_add_f32_e32 v93, v152, v93
	v_pk_mul_f32 v[156:157], v[130:131], v[130:131]
	v_add_f32_e32 v93, v153, v93
	v_add_f32_e32 v93, v156, v93
	v_pk_mul_f32 v[164:165], v[138:139], v[138:139]
	v_add_f32_e32 v93, v157, v93
	v_lshlrev_b32_e32 v166, 16, v86
	v_and_b32_e32 v167, 0xffff0000, v86
	v_add_f32_e32 v93, v164, v93
	v_pk_mul_f32 v[168:169], v[166:167], v[166:167]
	v_add_f32_e32 v93, v165, v93
	v_lshlrev_b32_e32 v86, 16, v87
	v_and_b32_e32 v87, 0xffff0000, v87
	v_add_f32_e32 v93, v168, v93
	v_pk_mul_f32 v[170:171], v[86:87], v[86:87]
	v_add_f32_e32 v93, v169, v93
	v_lshlrev_b32_e32 v172, 16, v88
	v_and_b32_e32 v173, 0xffff0000, v88
	v_add_f32_e32 v93, v170, v93
	v_pk_mul_f32 v[174:175], v[172:173], v[172:173]
	v_add_f32_e32 v93, v171, v93
	v_lshlrev_b32_e32 v88, 16, v89
	v_and_b32_e32 v89, 0xffff0000, v89
	v_add_f32_e32 v93, v174, v93
	v_pk_mul_f32 v[176:177], v[88:89], v[88:89]
	v_add_f32_e32 v93, v175, v93
	v_lshlrev_b32_e32 v178, 16, v82
	v_and_b32_e32 v179, 0xffff0000, v82
	v_add_f32_e32 v93, v176, v93
	v_pk_mul_f32 v[180:181], v[178:179], v[178:179]
	v_add_f32_e32 v93, v177, v93
	v_lshlrev_b32_e32 v82, 16, v83
	v_and_b32_e32 v83, 0xffff0000, v83
	v_add_f32_e32 v93, v180, v93
	v_pk_mul_f32 v[182:183], v[82:83], v[82:83]
	v_add_f32_e32 v93, v181, v93
	v_lshlrev_b32_e32 v184, 16, v84
	v_and_b32_e32 v185, 0xffff0000, v84
	v_add_f32_e32 v93, v182, v93
	v_pk_mul_f32 v[186:187], v[184:185], v[184:185]
	v_add_f32_e32 v93, v183, v93
	v_lshlrev_b32_e32 v84, 16, v85
	v_and_b32_e32 v85, 0xffff0000, v85
	v_add_f32_e32 v93, v186, v93
	v_pk_mul_f32 v[188:189], v[84:85], v[84:85]
	v_add_f32_e32 v93, v187, v93
	s_waitcnt vmcnt(16)
	v_lshlrev_b32_e32 v190, 16, v78
	v_and_b32_e32 v191, 0xffff0000, v78
	v_add_f32_e32 v93, v188, v93
	v_pk_mul_f32 v[192:193], v[190:191], v[190:191]
	v_add_f32_e32 v93, v189, v93
	v_lshlrev_b32_e32 v78, 16, v79
	v_and_b32_e32 v79, 0xffff0000, v79
	v_add_f32_e32 v93, v192, v93
	v_pk_mul_f32 v[194:195], v[78:79], v[78:79]
	v_add_f32_e32 v93, v193, v93
	v_lshlrev_b32_e32 v196, 16, v80
	v_and_b32_e32 v197, 0xffff0000, v80
	v_add_f32_e32 v93, v194, v93
	v_pk_mul_f32 v[198:199], v[196:197], v[196:197]
	v_add_f32_e32 v93, v195, v93
	v_lshlrev_b32_e32 v80, 16, v81
	v_and_b32_e32 v81, 0xffff0000, v81
	v_add_f32_e32 v93, v198, v93
	v_pk_mul_f32 v[200:201], v[80:81], v[80:81]
	v_add_f32_e32 v93, v199, v93
	v_lshlrev_b32_e32 v202, 16, v74
	v_and_b32_e32 v203, 0xffff0000, v74
	v_add_f32_e32 v93, v200, v93
	v_pk_mul_f32 v[204:205], v[202:203], v[202:203]
	v_add_f32_e32 v93, v201, v93
	v_lshlrev_b32_e32 v74, 16, v75
	v_and_b32_e32 v75, 0xffff0000, v75
	v_add_f32_e32 v93, v204, v93
	v_pk_mul_f32 v[206:207], v[74:75], v[74:75]
	v_add_f32_e32 v93, v205, v93
	v_lshlrev_b32_e32 v208, 16, v76
	v_and_b32_e32 v209, 0xffff0000, v76
	v_add_f32_e32 v93, v206, v93
	v_pk_mul_f32 v[210:211], v[208:209], v[208:209]
	v_add_f32_e32 v93, v207, v93
	v_lshlrev_b32_e32 v76, 16, v77
	v_and_b32_e32 v77, 0xffff0000, v77
	v_add_f32_e32 v93, v210, v93
	v_pk_mul_f32 v[212:213], v[76:77], v[76:77]
	v_add_f32_e32 v93, v211, v93
	v_lshlrev_b32_e32 v214, 16, v70
	v_and_b32_e32 v215, 0xffff0000, v70
	v_add_f32_e32 v93, v212, v93
	v_pk_mul_f32 v[216:217], v[214:215], v[214:215]
	v_add_f32_e32 v93, v213, v93
	v_lshlrev_b32_e32 v70, 16, v71
	v_and_b32_e32 v71, 0xffff0000, v71
	v_add_f32_e32 v93, v216, v93
	v_pk_mul_f32 v[218:219], v[70:71], v[70:71]
	v_add_f32_e32 v93, v217, v93
	v_lshlrev_b32_e32 v220, 16, v72
	v_and_b32_e32 v221, 0xffff0000, v72
	v_add_f32_e32 v93, v218, v93
	v_pk_mul_f32 v[222:223], v[220:221], v[220:221]
	v_add_f32_e32 v93, v219, v93
	v_lshlrev_b32_e32 v72, 16, v73
	v_and_b32_e32 v73, 0xffff0000, v73
	v_add_f32_e32 v93, v222, v93
	v_pk_mul_f32 v[224:225], v[72:73], v[72:73]
	v_add_f32_e32 v93, v223, v93
	v_lshlrev_b32_e32 v226, 16, v66
	v_and_b32_e32 v227, 0xffff0000, v66
	v_add_f32_e32 v93, v224, v93
	v_pk_mul_f32 v[228:229], v[226:227], v[226:227]
	v_add_f32_e32 v93, v225, v93
	v_lshlrev_b32_e32 v66, 16, v67
	v_and_b32_e32 v67, 0xffff0000, v67
	v_add_f32_e32 v93, v228, v93
	v_pk_mul_f32 v[230:231], v[66:67], v[66:67]
	v_add_f32_e32 v93, v229, v93
	v_lshlrev_b32_e32 v232, 16, v68
	v_and_b32_e32 v233, 0xffff0000, v68
	v_add_f32_e32 v93, v230, v93
	v_pk_mul_f32 v[234:235], v[232:233], v[232:233]
	v_add_f32_e32 v93, v231, v93
	v_lshlrev_b32_e32 v68, 16, v69
	v_and_b32_e32 v69, 0xffff0000, v69
	v_add_f32_e32 v93, v234, v93
	v_pk_mul_f32 v[236:237], v[68:69], v[68:69]
	v_add_f32_e32 v93, v235, v93
	v_add_f32_e32 v93, v236, v93
	v_add_f32_e32 v93, v237, v93
	v_fmamk_f32 v93, v93, 0x3c800000, v144
	v_mul_f32_e32 v97, 0x4b800000, v93
	v_cmp_gt_f32_e64 s[8:9], s39, v93
	v_sin_f32_e32 v91, v95
	v_sin_f32_e32 v92, v96
	v_cndmask_b32_e64 v93, v93, v97, s[8:9]
	v_rsq_f32_e32 v107, v93
	v_cvt_f32_f64_e32 v97, v[158:159]
	v_sin_f32_e32 v93, v97
	v_cos_f32_e32 v95, v95
	v_mul_f32_e32 v109, 0x45800000, v107
	v_cndmask_b32_e64 v134, v107, v109, s[8:9]
	v_pk_mul_f32 v[124:125], v[134:135], v[124:125] op_sel_hi:[0,1]
	s_waitcnt vmcnt(12)
	v_pk_mul_f32 v[62:63], v[62:63], v[124:125]
	v_pk_mul_f32 v[124:125], v[134:135], v[128:129] op_sel_hi:[0,1]
	v_pk_mul_f32 v[64:65], v[64:65], v[124:125]
	v_pk_mul_f32 v[124:125], v[134:135], v[132:133] op_sel_hi:[0,1]
	v_pk_mul_f32 v[58:59], v[58:59], v[124:125]
	v_pk_mul_f32 v[124:125], v[134:135], v[160:161] op_sel_hi:[0,1]
	v_pk_mul_f32 v[124:125], v[60:61], v[124:125]
	v_pk_mul_f32 v[60:61], v[134:135], v[122:123] op_sel_hi:[0,1]
	v_pk_mul_f32 v[54:55], v[54:55], v[60:61]
	v_pk_mul_f32 v[60:61], v[134:135], v[126:127] op_sel_hi:[0,1]
	v_pk_mul_f32 v[60:61], v[56:57], v[60:61]
	v_pk_mul_f32 v[56:57], v[134:135], v[130:131] op_sel_hi:[0,1]
	v_pk_mul_f32 v[122:123], v[46:47], v[56:57]
	v_pk_mul_f32 v[46:47], v[134:135], v[138:139] op_sel_hi:[0,1]
	v_pk_mul_f32 v[126:127], v[48:49], v[46:47]
	v_pk_mul_f32 v[46:47], v[134:135], v[166:167] op_sel_hi:[0,1]
	s_waitcnt vmcnt(8)
	v_pk_mul_f32 v[46:47], v[50:51], v[46:47]
	v_pk_mul_f32 v[50:51], v[134:135], v[172:173] op_sel_hi:[0,1]
	v_pk_mul_f32 v[42:43], v[42:43], v[50:51]
	v_pk_mul_f32 v[50:51], v[134:135], v[88:89] op_sel_hi:[0,1]
	v_pk_mul_f32 v[44:45], v[44:45], v[50:51]
	v_pk_mul_f32 v[50:51], v[134:135], v[178:179] op_sel_hi:[0,1]
	v_pk_mul_f32 v[38:39], v[38:39], v[50:51]
	v_pk_mul_f32 v[50:51], v[134:135], v[82:83] op_sel_hi:[0,1]
	v_pk_mul_f32 v[40:41], v[40:41], v[50:51]
	v_pk_mul_f32 v[50:51], v[134:135], v[184:185] op_sel_hi:[0,1]
	v_pk_mul_f32 v[30:31], v[30:31], v[50:51]
	v_pk_mul_f32 v[50:51], v[134:135], v[84:85] op_sel_hi:[0,1]
	v_pk_mul_f32 v[32:33], v[32:33], v[50:51]
	v_pk_mul_f32 v[50:51], v[134:135], v[190:191] op_sel_hi:[0,1]
	s_waitcnt vmcnt(4)
	v_pk_mul_f32 v[34:35], v[34:35], v[50:51]
	v_pk_mul_f32 v[50:51], v[134:135], v[78:79] op_sel_hi:[0,1]
	v_pk_mul_f32 v[36:37], v[36:37], v[50:51]
	v_pk_mul_f32 v[50:51], v[134:135], v[196:197] op_sel_hi:[0,1]
	v_pk_mul_f32 v[26:27], v[26:27], v[50:51]
	v_pk_mul_f32 v[50:51], v[134:135], v[80:81] op_sel_hi:[0,1]
	v_pk_mul_f32 v[28:29], v[28:29], v[50:51]
	v_pk_mul_f32 v[50:51], v[134:135], v[202:203] op_sel_hi:[0,1]
	v_pk_mul_f32 v[22:23], v[22:23], v[50:51]
	v_pk_mul_f32 v[50:51], v[134:135], v[74:75] op_sel_hi:[0,1]
	v_pk_mul_f32 v[24:25], v[24:25], v[50:51]
	v_pk_mul_f32 v[50:51], v[134:135], v[208:209] op_sel_hi:[0,1]
	v_pk_mul_f32 v[14:15], v[14:15], v[50:51]
	v_pk_mul_f32 v[50:51], v[134:135], v[76:77] op_sel_hi:[0,1]
	v_pk_mul_f32 v[16:17], v[16:17], v[50:51]
	v_pk_mul_f32 v[50:51], v[134:135], v[214:215] op_sel_hi:[0,1]
	s_waitcnt vmcnt(0)
	v_pk_mul_f32 v[18:19], v[18:19], v[50:51]
	v_pk_mul_f32 v[50:51], v[134:135], v[70:71] op_sel_hi:[0,1]
	v_pk_mul_f32 v[20:21], v[20:21], v[50:51]
	v_pk_mul_f32 v[50:51], v[134:135], v[220:221] op_sel_hi:[0,1]
	v_pk_mul_f32 v[10:11], v[10:11], v[50:51]
	v_pk_mul_f32 v[50:51], v[134:135], v[72:73] op_sel_hi:[0,1]
	v_pk_mul_f32 v[12:13], v[12:13], v[50:51]
	v_pk_mul_f32 v[50:51], v[134:135], v[226:227] op_sel_hi:[0,1]
	v_pk_mul_f32 v[6:7], v[6:7], v[50:51]
	v_pk_mul_f32 v[50:51], v[134:135], v[66:67] op_sel_hi:[0,1]
	v_pk_mul_f32 v[8:9], v[8:9], v[50:51]
	v_pk_mul_f32 v[50:51], v[134:135], v[232:233] op_sel_hi:[0,1]
	v_pk_mul_f32 v[2:3], v[2:3], v[50:51]
	v_pk_mul_f32 v[50:51], v[134:135], v[68:69] op_sel_hi:[0,1]
	v_pk_mul_f32 v[48:49], v[134:135], v[86:87] op_sel_hi:[0,1]
	v_pk_mul_f32 v[4:5], v[4:5], v[50:51]
	v_pk_mul_f32 v[50:51], v[114:115], v[54:55]
	v_cos_f32_e32 v96, v96
	v_cos_f32_e32 v97, v97
	v_pk_mul_f32 v[48:49], v[52:53], v[48:49]
	v_pk_fma_f32 v[52:53], v[116:117], v[62:63], v[50:51] neg_lo:[0,0,1] neg_hi:[0,0,1]
	v_pk_mul_f32 v[50:51], v[114:115], v[62:63]
	v_pk_mul_f32 v[62:63], v[92:93], v[126:127]
	v_pk_fma_f32 v[50:51], v[116:117], v[54:55], v[50:51]
	v_pk_mul_f32 v[54:55], v[118:119], v[60:61]
	v_lshl_add_u64 v[70:71], v[112:113], 0, s[20:21]
	v_pk_fma_f32 v[56:57], v[120:121], v[64:65], v[54:55] neg_lo:[0,0,1] neg_hi:[0,0,1]
	v_pk_mul_f32 v[54:55], v[118:119], v[64:65]
	v_pk_fma_f32 v[64:65], v[96:97], v[124:125], v[62:63] neg_lo:[0,0,1] neg_hi:[0,0,1]
	v_pk_fma_f32 v[54:55], v[120:121], v[60:61], v[54:55]
	v_pk_mul_f32 v[60:61], v[90:91], v[122:123]
	v_pk_mul_f32 v[62:63], v[92:93], v[124:125]
	v_pk_fma_f32 v[60:61], v[94:95], v[58:59], v[60:61] neg_lo:[0,0,1] neg_hi:[0,0,1]
	v_pk_mul_f32 v[58:59], v[90:91], v[58:59]
	v_pk_fma_f32 v[62:63], v[96:97], v[126:127], v[62:63]
	v_pk_fma_f32 v[58:59], v[94:95], v[122:123], v[58:59]
	v_cvt_pk_bf16_f32 v66, v52, v53
	v_cvt_pk_bf16_f32 v67, v56, v57
	v_cvt_pk_bf16_f32 v68, v60, v61
	v_cvt_pk_bf16_f32 v69, v64, v65
	global_store_dwordx4 v[70:71], v[66:69], off
	s_nop 1
	v_cvt_pk_bf16_f32 v66, v50, v51
	v_cvt_pk_bf16_f32 v67, v54, v55
	v_cvt_pk_bf16_f32 v68, v58, v59
	v_cvt_pk_bf16_f32 v69, v62, v63
	global_store_dwordx4 v[70:71], v[66:69], off offset:16
	s_nop 1
	v_cvt_pk_bf16_f32 v66, v46, v47
	v_cvt_pk_bf16_f32 v67, v48, v49
	v_cvt_pk_bf16_f32 v68, v42, v43
	v_cvt_pk_bf16_f32 v69, v44, v45
	global_store_dwordx4 v[70:71], v[66:69], off offset:32
	s_nop 1
	v_cvt_pk_bf16_f32 v66, v38, v39
	v_cvt_pk_bf16_f32 v67, v40, v41
	v_cvt_pk_bf16_f32 v68, v30, v31
	v_cvt_pk_bf16_f32 v69, v32, v33
	global_store_dwordx4 v[70:71], v[66:69], off offset:48
	s_nop 1
	v_cvt_pk_bf16_f32 v66, v34, v35
	v_cvt_pk_bf16_f32 v67, v36, v37
	v_cvt_pk_bf16_f32 v68, v26, v27
	v_cvt_pk_bf16_f32 v69, v28, v29
	global_store_dwordx4 v[70:71], v[66:69], off offset:64
	s_nop 1
	v_cvt_pk_bf16_f32 v66, v22, v23
	v_cvt_pk_bf16_f32 v67, v24, v25
	v_cvt_pk_bf16_f32 v68, v14, v15
	v_cvt_pk_bf16_f32 v69, v16, v17
	global_store_dwordx4 v[70:71], v[66:69], off offset:80
	s_nop 1
	v_cvt_pk_bf16_f32 v66, v18, v19
	v_cvt_pk_bf16_f32 v67, v20, v21
	v_cvt_pk_bf16_f32 v68, v10, v11
	v_cvt_pk_bf16_f32 v69, v12, v13
	global_store_dwordx4 v[70:71], v[66:69], off offset:96
	s_nop 1
	v_cvt_pk_bf16_f32 v66, v6, v7
	v_cvt_pk_bf16_f32 v67, v8, v9
	v_cvt_pk_bf16_f32 v68, v2, v3
	v_cvt_pk_bf16_f32 v69, v4, v5
	global_store_dwordx4 v[70:71], v[66:69], off offset:112
	s_and_saveexec_b64 s[8:9], s[4:5]
	s_cbranch_execz .LBB0_400
	ds_write2_b32 v145, v52, v53 offset1:1
	ds_write2_b32 v145, v56, v57 offset0:2 offset1:3
	ds_write2_b32 v145, v60, v61 offset0:4 offset1:5
	ds_write2_b32 v145, v64, v65 offset0:6 offset1:7
	ds_write2_b32 v145, v50, v51 offset0:8 offset1:9
	ds_write2_b32 v145, v54, v55 offset0:10 offset1:11
	ds_write2_b32 v145, v58, v59 offset0:12 offset1:13
	ds_write2_b32 v145, v62, v63 offset0:14 offset1:15
	ds_write2_b32 v145, v46, v47 offset0:16 offset1:17
	ds_write2_b32 v145, v48, v49 offset0:18 offset1:19
	ds_write2_b32 v145, v42, v43 offset0:20 offset1:21
	ds_write2_b32 v145, v44, v45 offset0:22 offset1:23
	ds_write2_b32 v145, v38, v39 offset0:24 offset1:25
	ds_write2_b32 v145, v40, v41 offset0:26 offset1:27
	ds_write2_b32 v145, v30, v31 offset0:28 offset1:29
	ds_write2_b32 v145, v32, v33 offset0:30 offset1:31
	ds_write2_b32 v145, v34, v35 offset0:32 offset1:33
	ds_write2_b32 v145, v36, v37 offset0:34 offset1:35
	ds_write2_b32 v145, v26, v27 offset0:36 offset1:37
	ds_write2_b32 v145, v28, v29 offset0:38 offset1:39
	ds_write2_b32 v145, v22, v23 offset0:40 offset1:41
	ds_write2_b32 v145, v24, v25 offset0:42 offset1:43
	ds_write2_b32 v145, v14, v15 offset0:44 offset1:45
	ds_write2_b32 v145, v16, v17 offset0:46 offset1:47
	ds_write2_b32 v145, v18, v19 offset0:48 offset1:49
	ds_write2_b32 v145, v20, v21 offset0:50 offset1:51
	ds_write2_b32 v145, v10, v11 offset0:52 offset1:53
	ds_write2_b32 v145, v12, v13 offset0:54 offset1:55
	ds_write2_b32 v145, v6, v7 offset0:56 offset1:57
	ds_write2_b32 v145, v8, v9 offset0:58 offset1:59
	ds_write2_b32 v145, v2, v3 offset0:60 offset1:61
	ds_write2_b32 v145, v4, v5 offset0:62 offset1:63

.LBB0_423:
	s_cmp_gt_i32 s70, 5
	s_cselect_b64 s[0:1], -1, 0
	s_cmp_lt_i32 s71, 6
	s_cselect_b64 s[2:3], -1, 0
	s_or_b64 s[0:1], s[0:1], s[2:3]
	s_and_b64 vcc, exec, s[0:1]
	s_cbranch_vccnz .LBB0_570
	s_cmp_lt_i32 s10, 32
	s_cbranch_scc1 .Lp5_body
	v_and_b32_e32 v1, 0x3ff, v0
	s_branch .Lmp_entry
.Lmp_done:
	s_waitcnt vmcnt(0) lgkmcnt(0)
	s_barrier
	v_and_b32_e32 v1, 0x3ff, v0
	v_cmp_eq_u32_e32 vcc, 0, v1
	s_and_saveexec_b64 s[2:3], vcc
	s_cbranch_execz .Lmp_arrived
	buffer_wbl2 sc1
	s_waitcnt vmcnt(0)
	v_mov_b32_e32 v2, 0x1ebaa800
	v_mov_b32_e32 v3, 1
	global_atomic_add v2, v3, s[68:69]

.Lp5_body:
	v_and_b32_e32 v138, 0x3ff, v0
	v_bfe_u32 v139, v0, 4, 2
	v_bfe_u32 v1, v138, 1, 3
	s_cmp_lt_i32 s10, 32
	v_and_b32_e32 v141, 15, v138
	v_xor_b32_e32 v4, v139, v1
	s_waitcnt lgkmcnt(0)
	v_bitop3_b32 v5, v139, v1, 4 bitop3:0x36
	v_bitop3_b32 v6, v139, v138, 15 bitop3:0x78
	s_cbranch_scc1 .LBB0_426
	v_and_b32_e32 v2, 15, v138
	v_bitop3_b32 v3, v139, v2, 4 bitop3:0x36
	v_lshlrev_b32_e32 v176, 4, v3
	v_bitop3_b32 v3, v139, v2, 8 bitop3:0x36
	v_lshlrev_b32_e32 v178, 4, v3
	v_bitop3_b32 v3, v139, v2, 12 bitop3:0x36
	v_and_b32_e32 v1, 0xff, v138
	v_lshlrev_b32_e32 v167, 7, v2
	v_lshlrev_b32_e32 v174, 4, v4
	v_lshlrev_b32_e32 v175, 4, v5
	v_lshlrev_b32_e32 v172, 8, v2
	v_lshlrev_b32_e32 v173, 4, v6
	v_lshlrev_b32_e32 v179, 4, v3
	v_and_b32_e32 v180, 63, v0
	v_lshlrev_b32_e32 v177, 2, v138
	s_cbranch_execz .LBB0_427
	s_branch .LBB0_462

.LBB0_462:
	v_cmp_eq_u32_e32 vcc, 0, v138
	s_and_saveexec_b64 s[2:3], vcc
	s_cbranch_execz .Lmp_wait_done
	s_sub_i32 s0, s11, 32
	v_mov_b32_e32 v3, 0x1ebaa800
.Lmp_poll:
	global_load_dword v4, v3, s[68:69] sc1
	s_waitcnt vmcnt(0)
	v_cmp_gt_u32_e32 vcc, s0, v4
	s_cbranch_vccz .Lmp_polled
	s_sleep 4
	s_branch .Lmp_poll
.Lmp_polled:
	buffer_inv sc1
	s_waitcnt vmcnt(0)
.Lmp_wait_done:
	s_or_b64 exec, exec, s[2:3]
	s_barrier
	s_load_dword s0, s[16:17], 0x10
	s_load_dword s2, s[16:17], 0x0
	s_add_u32 s66, s68, 0x1ebaa000
	v_lshrrev_b32_e32 v3, 6, v138
	v_lshrrev_b32_e32 v5, 3, v180
	s_addc_u32 s67, s69, 0
	s_waitcnt lgkmcnt(0)
	s_lshr_b32 s0, s0, 16
	v_lshl_or_b32 v4, v3, 3, v5
	s_cmp_lg_u32 s0, 0
	v_lshrrev_b32_e32 v6, 1, v4
	s_cselect_b64 s[0:1], -1, 0
	v_xor_b32_e32 v6, v6, v138
	s_cmp_lg_u64 s[0:1], 0
	v_lshlrev_b32_e32 v4, 9, v4
	v_lshlrev_b32_e32 v6, 3, v6
	s_addc_u32 s0, s2, 0
	v_and_or_b32 v4, v6, 56, v4
	v_lshlrev_b32_e32 v6, 2, v3
	s_max_i32 s0, s0, 32
	v_or_b32_e32 v7, v6, v139
	v_bitop3_b32 v6, v6, v138, v139 bitop3:0x36
	s_sub_i32 s33, s0, 32
	v_lshlrev_b32_e32 v7, 8, v7
	v_lshlrev_b32_e32 v6, 3, v6
	s_movk_i32 s0, 0x78
	v_and_or_b32 v6, v6, s0, v7
	v_add_u32_e32 v7, 8, v3
	v_lshl_or_b32 v5, v7, 3, v5
	v_lshrrev_b32_e32 v8, 1, v5
	v_xor_b32_e32 v8, v8, v138
	v_readlane_b32 s8, v246, 0
	v_lshlrev_b32_e32 v5, 9, v5
	v_lshlrev_b32_e32 v8, 3, v8
	v_readlane_b32 s9, v246, 1
	v_and_or_b32 v8, v8, 56, v5
	v_lshlrev_b32_e32 v5, 2, v7
	s_load_dwordx2 s[74:75], s[8:9], 0x90
	v_or_b32_e32 v7, v5, v139
	v_bitop3_b32 v5, v5, v138, v139 bitop3:0x36
	v_lshlrev_b32_e32 v7, 8, v7
	v_lshlrev_b32_e32 v5, 3, v5
	s_cmp_gt_i32 s10, 31
	v_and_or_b32 v10, v5, s0, v7
	s_movk_i32 s0, 0x100
	s_cselect_b64 s[6:7], -1, 0
	s_sub_i32 s83, s10, 32
	v_cmp_gt_u32_e64 s[4:5], s0, v138
	s_add_i32 s0, 0, 0x1cf00
	v_lshlrev_b32_e32 v5, 5, v3
	s_waitcnt lgkmcnt(0)
	s_add_u32 s90, s74, 0x2000000
	v_lshl_add_u32 v117, v3, 10, 0
	v_or_b32_e32 v152, v5, v2
	v_lshlrev_b32_e32 v3, 7, v3
	v_lshlrev_b32_e32 v2, 2, v2
	s_addc_u32 s91, s75, 0
	v_add_u32_e32 v153, s0, v177
	v_add3_u32 v155, s0, v3, v2
	s_add_u32 s0, s68, 0x1eb68000
	v_lshrrev_b32_e32 v154, 8, v138
	s_addc_u32 s93, s69, 0
	v_add_u32_e32 v2, 0, v177
	s_add_u32 s76, s68, 0xf000000
	v_add_u32_e32 v157, 0x18000, v2
	v_add_u32_e32 v158, 0x18800, v2
	v_lshlrev_b32_e32 v2, 2, v154
	s_addc_u32 s77, s69, 0
	v_lshl_or_b32 v2, v1, 6, v2
	s_add_u32 s78, s68, 0x1ebaa080
	v_add_u32_e32 v159, 0x18f00, v2
	v_lshl_add_u32 v2, v138, 6, 0
	v_lshlrev_b32_e32 v12, 3, v139
	s_addc_u32 s79, s69, 0
	v_add_u32_e32 v161, 0x18f0c, v2
	v_add_u32_e32 v162, 0x18f00, v2
	s_add_i32 s94, 0, 0x1d340
	v_mbcnt_lo_u32_b32 v2, -1, 0
	s_mov_b32 s73, 0
	v_cmp_eq_u32_e64 s[2:3], 0, v138
	v_mov_b32_e32 v115, 0
	v_or_b32_e32 v156, 31, v5
	v_lshlrev_b32_e32 v116, 2, v139
	v_add_u32_e32 v139, 0x200, v138
	v_and_b32_e32 v160, 0x300, v138
	v_mov_b32_e32 v163, s94
	v_add_u32_e32 v164, 0x4000, v117
	s_mov_b64 s[80:81], 0x100
	v_lshlrev_b32_e32 v118, 1, v12
	s_mov_b32 s82, 0x3e38aa3b
	v_lshlrev_b32_e32 v165, 1, v4
	v_lshlrev_b32_e32 v120, 1, v6
	v_lshlrev_b32_e32 v166, 1, v8
	v_lshlrev_b32_e32 v122, 1, v10
	s_movk_i32 s95, 0xffef
	v_add_u32_e32 v168, 0x2000, v117
	v_add_u32_e32 v169, 0x6000, v117
	v_mov_b32_e32 v170, 0xff800000
	v_mbcnt_hi_u32_b32 v171, -1, v2
	v_writelane_b32 v246, s0, 2
	s_branch .LBB0_465

	.amdhsa_kernel _Z10hymba_mega6Params
		.amdhsa_group_segment_fixed_size 0
		.amdhsa_private_segment_fixed_size 0
		.amdhsa_kernarg_size 424
		.amdhsa_user_sgpr_count 2
		.amdhsa_user_sgpr_dispatch_ptr 0
		.amdhsa_user_sgpr_queue_ptr 0
		.amdhsa_user_sgpr_kernarg_segment_ptr 1
		.amdhsa_user_sgpr_dispatch_id 0
		.amdhsa_user_sgpr_kernarg_preload_length 0
		.amdhsa_user_sgpr_kernarg_preload_offset 0
		.amdhsa_user_sgpr_private_segment_size 0
		.amdhsa_uses_dynamic_stack 0
		.amdhsa_enable_private_segment 0
		.amdhsa_system_sgpr_workgroup_id_x 1
		.amdhsa_system_sgpr_workgroup_id_y 0
		.amdhsa_system_sgpr_workgroup_id_z 0
		.amdhsa_system_sgpr_workgroup_info 0
		.amdhsa_system_vgpr_workitem_id 2
		.amdhsa_next_free_vgpr 247
		.amdhsa_next_free_sgpr 100
		.amdhsa_accum_offset 248
		.amdhsa_reserve_vcc 1
		.amdhsa_float_round_mode_32 0
		.amdhsa_float_round_mode_16_64 0
		.amdhsa_float_denorm_mode_32 3
		.amdhsa_float_denorm_mode_16_64 3
		.amdhsa_dx10_clamp 1
		.amdhsa_ieee_mode 1
		.amdhsa_fp16_overflow 0
		.amdhsa_tg_split 0
		.amdhsa_exception_fp_ieee_invalid_op 0
		.amdhsa_exception_fp_denorm_src 0
		.amdhsa_exception_fp_ieee_div_zero 0
		.amdhsa_exception_fp_ieee_overflow 0
		.amdhsa_exception_fp_ieee_underflow 0
		.amdhsa_exception_fp_ieee_inexact 0
		.amdhsa_exception_int_div_zero 0
	.end_amdhsa_kernel

amdhsa.kernels:
  - .agpr_count:     0
    .args:
      - .offset:         0
        .size:           168
        .value_kind:     by_value
      - .offset:         168
        .size:           4
        .value_kind:     hidden_block_count_x
      - .offset:         172
        .size:           4
        .value_kind:     hidden_block_count_y
      - .offset:         176
        .size:           4
        .value_kind:     hidden_block_count_z
      - .offset:         180
        .size:           2
        .value_kind:     hidden_group_size_x
      - .offset:         182
        .size:           2
        .value_kind:     hidden_group_size_y
      - .offset:         184
        .size:           2
        .value_kind:     hidden_group_size_z
      - .offset:         186
        .size:           2
        .value_kind:     hidden_remainder_x
      - .offset:         188
        .size:           2
        .value_kind:     hidden_remainder_y
      - .offset:         190
        .size:           2
        .value_kind:     hidden_remainder_z
      - .offset:         208
        .size:           8
        .value_kind:     hidden_global_offset_x
      - .offset:         216
        .size:           8
        .value_kind:     hidden_global_offset_y
      - .offset:         224
        .size:           8
        .value_kind:     hidden_global_offset_z
      - .offset:         232
        .size:           2
        .value_kind:     hidden_grid_dims
      - .offset:         256
        .size:           8
        .value_kind:     hidden_multigrid_sync_arg
      - .offset:         288
        .size:           4
        .value_kind:     hidden_dynamic_lds_size
    .group_segment_fixed_size: 0
    .kernarg_segment_align: 8
    .kernarg_segment_size: 424
    .language:       OpenCL C
    .language_version:
      - 2
      - 0
    .max_flat_workgroup_size: 512
    .name:           _Z10hymba_mega6Params
    .private_segment_fixed_size: 0
    .sgpr_count:     106
    .sgpr_spill_count: 3
    .symbol:         _Z10hymba_mega6Params.kd
    .uniform_work_group_size: 1
    .uses_dynamic_stack: false
    .vgpr_count:     247
    .vgpr_spill_count: 0
    .wavefront_size: 64
